# attention item prologue: SCHED codes loaded once per WG (lane-held), diagonal K-tile and kmax loads issued with the Q loads so the dependent global latencies overlap
# baseline (speedup 1.0000x reference)
.LBB0_564:
	s_mul_hi_i32 s2, s0, 6
	v_writelane_b32 v240, s0, 34
	s_mul_i32 s3, s0, 6
	s_getpc_b64 s[0:1]
	s_add_u32 s0, s0, _ZL5SCHED@rel32@lo+4
	s_addc_u32 s1, s1, _ZL5SCHED@rel32@hi+12
	s_add_u32 s38, s0, s3
	s_addc_u32 s39, s1, s2
	v_lshlrev_b32_e32 v243, 1, v147
	s_mov_b64 s[98:99], exec
	s_mov_b64 exec, 7
	global_load_ushort v242, v243, s[38:39]
	s_mov_b64 exec, s[98:99]
	s_waitcnt vmcnt(0)
	s_mov_b32 s20, s21
	s_branch .LBB0_567

.LBB0_567:
	s_nop 3
	v_readlane_b32 s0, v242, s20
	s_nop 1
	v_mov_b32_e32 v0, s0
	s_mov_b32 s0, 0xffff
	s_nop 0
	v_cmp_eq_u32_sdwa s[0:1], v0, s0 src0_sel:WORD_0 src1_sel:DWORD
	s_and_b64 vcc, exec, s[0:1]
	v_readfirstlane_b32 s0, v0
	s_cbranch_vccnz .LBB0_611
	s_and_b32 s30, 0xffff, s0
	s_and_b32 s4, s30, 63
	s_bfe_u32 s0, s30, 0x30006
	s_lshl_b32 s5, s4, 7
	s_lshl_b32 s2, s0, 8
	s_mov_b32 s3, s21
	v_or_b32_e32 v0, s5, v162
	v_lshl_add_u64 v[8:9], v[132:133], 0, s[2:3]
	v_lshlrev_b32_e32 v130, 11, v0
	v_or_b32_e32 v2, s5, v163
	v_lshl_add_u64 v[0:1], v[8:9], 0, v[130:131]
	v_lshlrev_b32_e32 v130, 11, v2
	v_or_b32_e32 v10, s5, v164
	v_lshl_add_u64 v[4:5], v[8:9], 0, v[130:131]
	v_lshlrev_b32_e32 v130, 11, v10
	v_lshl_add_u64 v[10:11], v[8:9], 0, v[130:131]
	v_add_lshl_u32 v130, s5, v165, 11
	v_lshl_add_u64 v[12:13], v[8:9], 0, v[130:131]
	global_load_dwordx4 v[0:3], v[0:1], off
	s_nop 0
	global_load_dwordx4 v[4:7], v[4:5], off
	s_nop 0
	global_load_dwordx4 v[8:11], v[10:11], off
	s_nop 0
	global_load_dwordx4 v[12:15], v[12:13], off
	s_lshl_b32 s98, s0, 8
	s_mov_b32 s99, 0
	v_lshl_add_u64 v[114:115], v[134:135], 0, s[98:99]
	s_lshl_b32 s98, s4, 1
	s_or_b32 s98, s98, 1
	s_lshl_b32 s98, s98, 17
	v_lshl_add_u64 v[116:117], v[114:115], 0, s[98:99]
	s_lshl_b32 s98, s4, 18
	v_lshl_add_u64 v[118:119], v[114:115], 0, s[98:99]
	s_mov_b64 s[100:101], 0x2000
	global_load_dwordx4 v[96:99], v[116:117], off
	global_load_dwordx4 v[104:107], v[118:119], off
	v_lshl_add_u64 v[116:117], v[116:117], 0, s[100:101]
	v_lshl_add_u64 v[118:119], v[118:119], 0, s[100:101]
	global_load_dwordx4 v[100:103], v[116:117], off
	global_load_dwordx4 v[108:111], v[118:119], off
	v_readlane_b32 s1, v240, 20
	s_lshl_b32 s1, s1, 2
	s_lshl_b32 s2, s0, 6
	s_or_b32 s1, s2, s1
	v_mov_b32_e32 v16, s1
	s_mul_i32 s1, s0, 23
	s_add_i32 s1, s1, s4
	v_sub_co_u32_e64 v18, s[8:9], s1, v185
	s_add_i32 s1, s0, 1
	v_readfirstlane_b32 s31, v18
	s_lshl_b32 s11, s0, 7
	global_load_dwordx4 v[120:123], v16, s[28:29] offset:16
	global_load_dwordx4 v[124:127], v16, s[28:29]
	s_waitcnt vmcnt(9)
	ds_write_b128 v176, v[0:3]
	s_waitcnt vmcnt(8)
	ds_write_b128 v177, v[4:7]
	s_waitcnt vmcnt(7)
	ds_write_b128 v178, v[8:11]
	s_waitcnt vmcnt(6)
	ds_write_b128 v179, v[12:15]
	s_waitcnt lgkmcnt(0)
	s_barrier
	s_nop 0
	s_nop 0
	ds_read_b128 v[8:11], v186
	ds_read_b128 v[12:15], v186 offset:4128
	s_waitcnt lgkmcnt(1)
	v_lshlrev_b32_e32 v16, 16, v8
	v_and_b32_e32 v8, 0xffff0000, v8
	v_mul_f32_e32 v8, v8, v8
	v_fmac_f32_e32 v8, v16, v16
	v_lshlrev_b32_e32 v16, 16, v9
	v_fmac_f32_e32 v8, v16, v16
	v_and_b32_e32 v9, 0xffff0000, v9
	v_fmac_f32_e32 v8, v9, v9
	v_lshlrev_b32_e32 v9, 16, v10
	v_fmac_f32_e32 v8, v9, v9
	v_and_b32_e32 v9, 0xffff0000, v10
	v_fmac_f32_e32 v8, v9, v9
	v_lshlrev_b32_e32 v9, 16, v11
	v_fmac_f32_e32 v8, v9, v9
	v_and_b32_e32 v9, 0xffff0000, v11
	v_fmac_f32_e32 v8, v9, v9
	s_waitcnt lgkmcnt(0)
	v_lshlrev_b32_e32 v9, 16, v12
	v_fmac_f32_e32 v8, v9, v9
	v_and_b32_e32 v9, 0xffff0000, v12
	v_fmac_f32_e32 v8, v9, v9
	v_lshlrev_b32_e32 v9, 16, v13
	v_fmac_f32_e32 v8, v9, v9
	v_and_b32_e32 v9, 0xffff0000, v13
	ds_read_b128 v[10:13], v186 offset:8256
	v_fmac_f32_e32 v8, v9, v9
	v_lshlrev_b32_e32 v9, 16, v14
	v_fmac_f32_e32 v8, v9, v9
	v_and_b32_e32 v9, 0xffff0000, v14
	v_fmac_f32_e32 v8, v9, v9
	v_lshlrev_b32_e32 v9, 16, v15
	v_fmac_f32_e32 v8, v9, v9
	v_and_b32_e32 v9, 0xffff0000, v15
	v_fmac_f32_e32 v8, v9, v9
	ds_read_b128 v[14:17], v186 offset:12384
	s_waitcnt lgkmcnt(1)
	v_lshlrev_b32_e32 v9, 16, v10
	v_fmac_f32_e32 v8, v9, v9
	v_and_b32_e32 v9, 0xffff0000, v10
	v_fmac_f32_e32 v8, v9, v9
	v_lshlrev_b32_e32 v9, 16, v11
	v_fmac_f32_e32 v8, v9, v9
	v_and_b32_e32 v9, 0xffff0000, v11
	v_fmac_f32_e32 v8, v9, v9
	v_lshlrev_b32_e32 v9, 16, v12
	v_fmac_f32_e32 v8, v9, v9
	v_and_b32_e32 v9, 0xffff0000, v12
	v_fmac_f32_e32 v8, v9, v9
	v_lshlrev_b32_e32 v9, 16, v13
	v_fmac_f32_e32 v8, v9, v9
	v_and_b32_e32 v9, 0xffff0000, v13
	v_fmac_f32_e32 v8, v9, v9
	s_waitcnt lgkmcnt(0)
	v_lshlrev_b32_e32 v9, 16, v14
	v_fmac_f32_e32 v8, v9, v9
	v_and_b32_e32 v9, 0xffff0000, v14
	v_fmac_f32_e32 v8, v9, v9
	v_lshlrev_b32_e32 v9, 16, v15
	v_fmac_f32_e32 v8, v9, v9
	v_and_b32_e32 v9, 0xffff0000, v15
	v_fmac_f32_e32 v8, v9, v9
	v_lshlrev_b32_e32 v9, 16, v16
	v_fmac_f32_e32 v8, v9, v9
	v_and_b32_e32 v9, 0xffff0000, v16
	v_fmac_f32_e32 v8, v9, v9
	v_lshlrev_b32_e32 v9, 16, v17
	v_fmac_f32_e32 v8, v9, v9
	v_and_b32_e32 v9, 0xffff0000, v17
	v_fmac_f32_e32 v8, v9, v9
	ds_bpermute_b32 v9, v159, v8
	v_cvt_f32_ubyte0_e32 v10, s1
	s_mov_b64 s[0:1], exec
	v_readlane_b32 s2, v241, 3
	v_readlane_b32 s3, v241, 4
	s_and_b64 s[2:3], s[0:1], s[2:3]
	s_mov_b64 exec, s[2:3]
	v_mov_b32_e32 v11, s71
	ds_write_b32 v11, v180
	s_or_b64 exec, exec, s[0:1]
	s_waitcnt vmcnt(0)
	v_mov_b32_e32 v0, v120
	v_mov_b32_e32 v1, v121
	v_mov_b32_e32 v2, v122
	v_mov_b32_e32 v3, v123
	v_mov_b32_e32 v4, v124
	v_mov_b32_e32 v5, v125
	v_mov_b32_e32 v6, v126
	v_mov_b32_e32 v7, v127
	v_add_f32_e32 v4, 0, v4
	v_add_f32_e32 v4, v4, v5
	v_add_f32_e32 v4, v4, v6
	v_add_f32_e32 v4, v4, v7
	v_add_f32_e32 v0, v4, v0
	v_add_f32_e32 v0, v0, v1
	v_readlane_b32 s0, v241, 37
	v_add_f32_e32 v0, v0, v2
	s_lshl_b32 s10, s4, 1
	s_add_i32 s2, s5, s0
	v_add_f32_e32 v0, v0, v3
	v_readlane_b32 s0, v240, 30
	s_waitcnt lgkmcnt(0)
	v_add_f32_e32 v1, v8, v9
	s_add_i32 s14, s10, s0
	v_mul_f32_e32 v0, v0, v1
	s_mov_b32 s0, 0xf800000
	v_cmp_gt_f32_e32 vcc, s0, v0
	v_mul_f32_e32 v1, 0x4f800000, v0
	v_exp_f32_e64 v10, -v10
	v_cndmask_b32_e32 v0, v0, v1, vcc
	v_sqrt_f32_e32 v1, v0
	s_or_b32 s12, s10, 1
	s_lshl_b32 s80, s11, 1
	s_mov_b32 s81, s21
	v_add_u32_e32 v2, -1, v1
	v_fma_f32 v3, -v2, v1, v0
	v_cmp_ge_f32_e64 s[0:1], 0, v3
	v_add_u32_e32 v3, 1, v1
	v_lshl_add_u64 v[112:113], v[134:135], 0, s[80:81]
	v_cndmask_b32_e64 v2, v1, v2, s[0:1]
	v_fma_f32 v1, -v3, v1, v0
	v_cmp_lt_f32_e64 s[0:1], 0, v1
	s_movk_i32 s3, 0x2000
	v_mul_f32_e32 v129, 0x3fb8aa3b, v10
	v_cndmask_b32_e64 v1, v2, v3, s[0:1]
	v_mul_f32_e32 v2, 0x37800000, v1
	s_lshl_b32 s0, s12, 17
	s_mov_b32 s1, s21
	v_cndmask_b32_e32 v1, v1, v2, vcc
	v_cmp_class_f32_e32 vcc, v0, v181
	v_lshl_add_u64 v[4:5], v[112:113], 0, s[0:1]
	s_lshl_b32 s0, s4, 18
	v_cndmask_b32_e32 v0, v1, v0, vcc
	v_lshl_add_u64 v[12:13], v[112:113], 0, s[0:1]
	v_fmamk_f32 v32, v0, 0x3f804189, v182
	s_nop 0
	s_nop 0
	v_add_co_u32_e32 v4, vcc, s3, v4
	v_readlane_b32 s0, v240, 21
	s_nop 0
	v_addc_co_u32_e32 v5, vcc, 0, v5, vcc
	s_nop 0
	v_add_co_u32_e32 v12, vcc, s3, v12
	v_add_u32_e32 v145, 0x100, v170
	s_nop 0
	v_addc_co_u32_e32 v13, vcc, 0, v13, vcc
	s_nop 0
	v_add_u32_e32 v33, s0, v166
	s_lshl_b32 s0, s14, 6
	v_or_b32_e32 v148, s2, v161
	s_waitcnt vmcnt(3)
	ds_write_b128 v145, v[96:99]
	s_waitcnt vmcnt(1)
	ds_write_b128 v145, v[100:103] offset:64
	ds_write_b128 v145, v[104:107] offset:33280
	s_waitcnt vmcnt(0)
	ds_write_b128 v145, v[108:111] offset:33344
	s_waitcnt lgkmcnt(0)
	s_barrier
	ds_read_b128 v[0:3], v33
	ds_read_b128 v[4:7], v33 offset:512
	ds_read_b128 v[8:11], v186
	s_waitcnt lgkmcnt(0)
	v_mfma_f32_32x32x16_bf16 v[16:31], v[0:3], v[8:11], 0
	ds_read_b128 v[34:37], v33 offset:2080
	ds_read_b128 v[38:41], v33 offset:2592
	ds_read_b128 v[42:45], v186 offset:4128
	v_mfma_f32_32x32x16_bf16 v[0:15], v[4:7], v[8:11], 0
	s_waitcnt lgkmcnt(0)
	v_mfma_f32_32x32x16_bf16 v[16:31], v[34:37], v[42:45], v[16:31]
	v_mfma_f32_32x32x16_bf16 v[0:15], v[38:41], v[42:45], v[0:15]
	ds_read_b128 v[34:37], v33 offset:4160
	ds_read_b128 v[38:41], v33 offset:4672
	ds_read_b128 v[42:45], v186 offset:8256
	s_waitcnt lgkmcnt(0)
	v_mfma_f32_32x32x16_bf16 v[16:31], v[34:37], v[42:45], v[16:31]
	v_mfma_f32_32x32x16_bf16 v[0:15], v[38:41], v[42:45], v[0:15]
	ds_read_b128 v[34:37], v33 offset:6240
	ds_read_b128 v[38:41], v33 offset:6752
	ds_read_b128 v[42:45], v186 offset:12384
	v_subrev_u32_e32 v33, s0, v171
	v_add_u32_e32 v33, v33, v148
	v_cvt_f32_i32_e32 v33, v33
	s_mov_b32 s0, 0xff61b1e6
	s_waitcnt lgkmcnt(0)
	v_mfma_f32_32x32x16_bf16 v[16:31], v[34:37], v[42:45], v[16:31]
	v_add_f32_e32 v34, 0xc2000000, v33
	v_mfma_f32_32x32x16_bf16 v[0:15], v[38:41], v[42:45], v[0:15]
	s_nop 9
	v_fma_f32 v16, -v129, |v33|, v16
	s_nop 0
	v_fma_f32 v0, -v129, |v34|, v0
	v_max_f32_e32 v0, v16, v0
	v_add_f32_e32 v16, -1.0, v33
	v_fma_f32 v16, -v129, |v16|, v17
	v_add_f32_e32 v17, 0xc2040000, v33
	v_fma_f32 v1, -v129, |v17|, v1
	v_max_f32_e32 v1, v16, v1
	v_max3_f32 v0, v0, s0, v1
	v_add_f32_e32 v1, -2.0, v33
	v_add_f32_e32 v16, 0xc2080000, v33
	v_fma_f32 v1, -v129, |v1|, v18
	v_fma_f32 v2, -v129, |v16|, v2
	v_max_f32_e32 v1, v1, v2
	v_add_f32_e32 v2, 0xc0400000, v33
	v_add_f32_e32 v16, 0xc20c0000, v33
	v_fma_f32 v2, -v129, |v2|, v19
	v_fma_f32 v3, -v129, |v16|, v3
	v_max_f32_e32 v2, v2, v3
	v_max3_f32 v0, v0, v1, v2
	v_add_f32_e32 v1, -4.0, v33
	v_add_f32_e32 v2, 0xc2100000, v33
	v_fma_f32 v1, -v129, |v1|, v20
	v_fma_f32 v2, -v129, |v2|, v4
	v_max_f32_e32 v1, v1, v2
	v_add_f32_e32 v2, 0xc0a00000, v33
	v_add_f32_e32 v3, 0xc2140000, v33
	v_fma_f32 v2, -v129, |v2|, v21
	v_fma_f32 v3, -v129, |v3|, v5
	v_max_f32_e32 v2, v2, v3
	v_max3_f32 v0, v0, v1, v2
	v_add_f32_e32 v1, 0xc0c00000, v33
	v_add_f32_e32 v2, 0xc2180000, v33
	v_fma_f32 v1, -v129, |v1|, v22
	v_fma_f32 v2, -v129, |v2|, v6
	v_max_f32_e32 v1, v1, v2
	v_add_f32_e32 v2, 0xc0e00000, v33
	v_add_f32_e32 v3, 0xc21c0000, v33
	v_fma_f32 v2, -v129, |v2|, v23
	v_fma_f32 v3, -v129, |v3|, v7
	v_max_f32_e32 v2, v2, v3
	v_max3_f32 v0, v0, v1, v2
	v_add_f32_e32 v1, 0xc1800000, v33
	v_add_f32_e32 v2, 0xc2400000, v33
	v_fma_f32 v1, -v129, |v1|, v24
	v_fma_f32 v2, -v129, |v2|, v8
	v_max_f32_e32 v1, v1, v2
	v_add_f32_e32 v2, 0xc1880000, v33
	v_add_f32_e32 v3, 0xc2440000, v33
	v_fma_f32 v2, -v129, |v2|, v25
	v_fma_f32 v3, -v129, |v3|, v9
	v_max_f32_e32 v2, v2, v3
	v_max3_f32 v0, v0, v1, v2
	v_add_f32_e32 v1, 0xc1900000, v33
	v_add_f32_e32 v2, 0xc2480000, v33
	v_fma_f32 v1, -v129, |v1|, v26
	v_fma_f32 v2, -v129, |v2|, v10
	v_max_f32_e32 v1, v1, v2
	v_add_f32_e32 v2, 0xc1980000, v33
	v_add_f32_e32 v3, 0xc24c0000, v33
	v_fma_f32 v2, -v129, |v2|, v27
	v_fma_f32 v3, -v129, |v3|, v11
	v_max_f32_e32 v2, v2, v3
	v_max3_f32 v0, v0, v1, v2
	v_add_f32_e32 v1, 0xc1a00000, v33
	v_add_f32_e32 v2, 0xc2500000, v33
	v_fma_f32 v1, -v129, |v1|, v28
	v_fma_f32 v2, -v129, |v2|, v12
	v_max_f32_e32 v1, v1, v2
	v_add_f32_e32 v2, 0xc1a80000, v33
	v_add_f32_e32 v3, 0xc2540000, v33
	v_fma_f32 v2, -v129, |v2|, v29
	v_fma_f32 v3, -v129, |v3|, v13
	v_max_f32_e32 v2, v2, v3
	v_max3_f32 v0, v0, v1, v2
	v_add_f32_e32 v1, 0xc1b00000, v33
	v_add_f32_e32 v2, 0xc2580000, v33
	v_fma_f32 v1, -v129, |v1|, v30
	v_fma_f32 v2, -v129, |v2|, v14
	v_max_f32_e32 v1, v1, v2
	v_add_f32_e32 v2, 0xc1b80000, v33
	v_add_f32_e32 v3, 0xc25c0000, v33
	v_fma_f32 v2, -v129, |v2|, v31
	v_fma_f32 v3, -v129, |v3|, v15
	v_max_f32_e32 v2, v2, v3
	v_max3_f32 v0, v0, v1, v2
	ds_bpermute_b32 v1, v159, v0
	s_waitcnt lgkmcnt(0)
	v_max_f32_e32 v1, v1, v1
	v_max_f32_e32 v149, v0, v1
	v_sub_f32_e32 v0, v32, v149
	ds_bpermute_b32 v1, v154, v0
	s_waitcnt lgkmcnt(0)
	v_max_f32_e32 v1, v1, v1
	v_max_f32_e32 v0, v0, v1
	ds_bpermute_b32 v1, v155, v0
	s_waitcnt lgkmcnt(0)
	v_max_f32_e32 v1, v1, v1
	v_max_f32_e32 v0, v0, v1
	ds_bpermute_b32 v1, v156, v0
	s_waitcnt lgkmcnt(0)
	v_max_f32_e32 v1, v1, v1
	v_max_f32_e32 v0, v0, v1
	ds_bpermute_b32 v1, v157, v0
	s_waitcnt lgkmcnt(0)
	v_max_f32_e32 v1, v1, v1
	v_max_f32_e32 v0, v0, v1
	ds_bpermute_b32 v1, v158, v0
	s_mov_b64 s[0:1], exec
	v_readlane_b32 s16, v240, 32
	v_readlane_b32 s17, v240, 33
	s_and_b64 s[16:17], s[0:1], s[16:17]
	s_mov_b64 exec, s[16:17]
	s_cbranch_execz .LBB0_575
	s_waitcnt lgkmcnt(0)
	v_max_f32_e32 v1, v1, v1
	v_max_f32_e32 v0, v0, v0
	v_max_f32_e32 v0, v0, v1
	s_sub_i32 s2, s2, 63
	v_add_f32_e32 v0, 0x43080000, v0
	v_cvt_f32_i32_e32 v1, s2
	v_div_scale_f32 v2, s[2:3], v129, v129, v0
	v_rcp_f32_e32 v3, v2
	s_brev_b32 s13, -2
	s_mov_b64 s[2:3], exec
	v_fma_f32 v4, -v2, v3, 1.0
	v_fmac_f32_e32 v3, v4, v3
	v_div_scale_f32 v4, vcc, v0, v129, v0
	v_mul_f32_e32 v5, v4, v3
	v_fma_f32 v6, -v2, v5, v4
	v_fmac_f32_e32 v5, v6, v3
	v_fma_f32 v2, -v2, v5, v4
	v_div_fmas_f32 v2, v2, v3, v5
	v_div_fixup_f32 v0, v2, v129, v0
	v_sub_f32_e32 v0, v1, v0
	v_mul_f32_e32 v0, 0x3c800000, v0
	v_ceil_f32_e32 v1, v0
	v_cvt_i32_f32_e32 v1, v1
	v_cmp_lt_f32_e32 vcc, 0, v0
	s_nop 1
	v_cndmask_b32_e32 v0, 0, v1, vcc

	.amdhsa_kernel _Z10fwd_kernel4Args
		.amdhsa_group_segment_fixed_size 256
		.amdhsa_private_segment_fixed_size 0
		.amdhsa_kernarg_size 472
		.amdhsa_user_sgpr_count 2
		.amdhsa_user_sgpr_dispatch_ptr 0
		.amdhsa_user_sgpr_queue_ptr 0
		.amdhsa_user_sgpr_kernarg_segment_ptr 1
		.amdhsa_user_sgpr_dispatch_id 0
		.amdhsa_user_sgpr_kernarg_preload_length 0
		.amdhsa_user_sgpr_kernarg_preload_offset 0
		.amdhsa_user_sgpr_private_segment_size 0
		.amdhsa_uses_dynamic_stack 0
		.amdhsa_enable_private_segment 0
		.amdhsa_system_sgpr_workgroup_id_x 1
		.amdhsa_system_sgpr_workgroup_id_y 0
		.amdhsa_system_sgpr_workgroup_id_z 0
		.amdhsa_system_sgpr_workgroup_info 0
		.amdhsa_system_vgpr_workitem_id 2
		.amdhsa_next_free_vgpr 244
		.amdhsa_next_free_sgpr 102
		.amdhsa_accum_offset 244
		.amdhsa_reserve_vcc 1
		.amdhsa_float_round_mode_32 0
		.amdhsa_float_round_mode_16_64 0
		.amdhsa_float_denorm_mode_32 3
		.amdhsa_float_denorm_mode_16_64 3
		.amdhsa_dx10_clamp 1
		.amdhsa_ieee_mode 1
		.amdhsa_fp16_overflow 0
		.amdhsa_tg_split 0
		.amdhsa_exception_fp_ieee_invalid_op 0
		.amdhsa_exception_fp_denorm_src 0
		.amdhsa_exception_fp_ieee_div_zero 0
		.amdhsa_exception_fp_ieee_overflow 0
		.amdhsa_exception_fp_ieee_underflow 0
		.amdhsa_exception_fp_ieee_inexact 0
		.amdhsa_exception_int_div_zero 0
	.end_amdhsa_kernel

amdhsa.kernels:
  - .agpr_count:     0
    .args:
      - .offset:         0
        .size:           216
        .value_kind:     by_value
      - .offset:         216
        .size:           4
        .value_kind:     hidden_block_count_x
      - .offset:         220
        .size:           4
        .value_kind:     hidden_block_count_y
      - .offset:         224
        .size:           4
        .value_kind:     hidden_block_count_z
      - .offset:         228
        .size:           2
        .value_kind:     hidden_group_size_x
      - .offset:         230
        .size:           2
        .value_kind:     hidden_group_size_y
      - .offset:         232
        .size:           2
        .value_kind:     hidden_group_size_z
      - .offset:         234
        .size:           2
        .value_kind:     hidden_remainder_x
      - .offset:         236
        .size:           2
        .value_kind:     hidden_remainder_y
      - .offset:         238
        .size:           2
        .value_kind:     hidden_remainder_z
      - .offset:         256
        .size:           8
        .value_kind:     hidden_global_offset_x
      - .offset:         264
        .size:           8
        .value_kind:     hidden_global_offset_y
      - .offset:         272
        .size:           8
        .value_kind:     hidden_global_offset_z
      - .offset:         280
        .size:           2
        .value_kind:     hidden_grid_dims
      - .offset:         304
        .size:           8
        .value_kind:     hidden_multigrid_sync_arg
      - .offset:         336
        .size:           4
        .value_kind:     hidden_dynamic_lds_size
    .group_segment_fixed_size: 256
    .kernarg_segment_align: 8
    .kernarg_segment_size: 472
    .language:       OpenCL C
    .language_version:
      - 2
      - 0
    .max_flat_workgroup_size: 512
    .name:           _Z10fwd_kernel4Args
    .private_segment_fixed_size: 0
    .sgpr_count:     108
    .sgpr_spill_count: 103
    .symbol:         _Z10fwd_kernel4Args.kd
    .uniform_work_group_size: 1
    .uses_dynamic_stack: false
    .vgpr_count:     244
    .vgpr_spill_count: 0
    .wavefront_size: 64
